# v20 plus dead-code removal in pass A (leftover IEEE sqrt/div_scale chain whose only consumer was a don't-care pack operand, 24 VALU per unit)
# speedup vs baseline: 1.0080x; 1.0020x over previous
.LBB0_698:
	v_cndmask_b32_e64 v29, v34, 0, s[24:25]
	v_readlane_b32 s80, v233, 39
	v_add_f32_e32 v34, v35, v29
	v_readlane_b32 s81, v233, 40
	v_readlane_b32 s0, v233, 41
	v_readlane_b32 s1, v233, 42
	v_cndmask_b32_e64 v29, v29, v34, s[80:81]
	v_add_f32_e32 v32, v32, v29
	v_cndmask_b32_e64 v29, v29, v32, s[0:1]
	v_readlane_b32 s0, v233, 43
	v_add_f32_e32 v32, v33, v29
	v_readlane_b32 s1, v233, 44
	s_nop 1
	v_cndmask_b32_e64 v29, v29, v32, s[0:1]
	v_readlane_b32 s0, v233, 45
	v_add_f32_e32 v30, v30, v29
	v_readlane_b32 s1, v233, 46
	s_nop 0
	s_nop 0
	v_cndmask_b32_e64 v29, v29, v30, s[0:1]
	v_readlane_b32 s0, v233, 47
	v_add_f32_e32 v31, v31, v29
	v_readlane_b32 s1, v233, 48
	s_nop 1
	v_cndmask_b32_e64 v29, v29, v31, s[0:1]
	v_add_f32_e32 v18, v18, v29
	s_nop 1
	s_nop 0
	v_readlane_b32 s0, v233, 49
	v_readlane_b32 s1, v233, 50
	s_nop 1
	v_cndmask_b32_e64 v18, v29, v18, s[0:1]
	v_readlane_b32 s0, v233, 51
	v_add_f32_e32 v19, v19, v18
	v_readlane_b32 s1, v233, 52
	s_nop 1
	v_cndmask_b32_e64 v18, v18, v19, s[0:1]
	v_sqrt_f32_e32 v19, s46
	s_nop 0
	v_max_f32_e32 v19, 0x2b8cbccc, v19
	v_rcp_f32_e32 v19, v19
	s_nop 0
	v_mul_f32_e32 v19, v112, v19
	v_add_f32_e32 v109, v109, v18
	v_mul_f32_e32 v17, v19, v17
	v_sqrt_f32_e32 v29, s19
	s_nop 0
	v_max_f32_e32 v29, 0x2b8cbccc, v29
	v_rcp_f32_e32 v29, v29
	s_nop 0
	v_mul_f32_e32 v29, v111, v29
	v_mul_f32_e32 v15, v29, v15
	s_nop 0
	v_sqrt_f32_e32 v30, s18
	s_nop 0
	v_max_f32_e32 v30, 0x2b8cbccc, v30
	v_rcp_f32_e32 v30, v30
	s_nop 0
	v_mul_f32_e32 v114, v110, v30
	v_mul_f32_e32 v16, v114, v16
	s_nop 0
	v_sqrt_f32_e32 v30, s17
	s_nop 0
	v_max_f32_e32 v30, 0x2b8cbccc, v30
	v_rcp_f32_e32 v30, v30
	s_nop 0
	v_mul_f32_e32 v104, v104, v30
	v_mul_f32_e32 v14, v104, v14
	s_nop 0
	v_sqrt_f32_e32 v30, s9
	s_nop 0
	v_max_f32_e32 v30, 0x2b8cbccc, v30
	v_rcp_f32_e32 v30, v30
	s_nop 0
	v_mul_f32_e32 v100, v100, v30
	v_mul_f32_e32 v13, v100, v13
	s_nop 0
	v_sqrt_f32_e32 v30, s8
	s_nop 0
	v_max_f32_e32 v30, 0x2b8cbccc, v30
	v_rcp_f32_e32 v30, v30
	s_nop 0
	v_mul_f32_e32 v115, v99, v30
	v_lshlrev_b32_e32 v110, 16, v61
	v_mul_f32_e32 v11, v115, v11
	s_nop 0
	v_and_b32_e32 v31, 0xffff0000, v88
	v_sqrt_f32_e32 v30, s7
	s_nop 0
	v_max_f32_e32 v30, 0x2b8cbccc, v30
	v_rcp_f32_e32 v30, v30
	s_nop 0
	v_mul_f32_e32 v116, v98, v30
	v_lshlrev_b32_e32 v30, 16, v88
	v_lshlrev_b32_e32 v33, 16, v54
	v_lshlrev_b32_e32 v35, 16, v52
	v_lshlrev_b32_e32 v34, 16, v45
	v_mov_b32_e32 v32, v31
	v_pk_add_f32 v[30:31], v[30:31], v[34:35] neg_lo:[0,1] neg_hi:[0,1]
	v_pk_add_f32 v[98:99], v[34:35], v[32:33] neg_lo:[0,1] neg_hi:[0,1]
	v_pk_fma_f32 v[30:31], v[24:25], v[30:31], v[34:35] op_sel_hi:[0,1,1]
	v_pk_fma_f32 v[34:35], v[98:99], v[24:25], v[32:33] op_sel_hi:[1,0,1]
	v_mul_f32_e32 v32, s6, v79
	v_lshlrev_b32_e32 v99, 16, v66
	v_lshlrev_b32_e32 v98, 16, v56
	v_lshlrev_b32_e32 v111, 16, v71
	v_pk_mov_b32 v[32:33], v[32:33], v[110:111] op_sel:[1,0]
	v_mul_f32_e32 v12, v116, v12
	v_pk_add_f32 v[32:33], v[32:33], v[98:99] neg_lo:[0,1] neg_hi:[0,1]
	v_pk_fma_f32 v[32:33], v[32:33], v[24:25], v[98:99] op_sel_hi:[1,0,1]
	s_nop 0
	s_nop 1
	v_pk_add_f32 v[112:113], v[98:99], v[110:111] neg_lo:[0,1] neg_hi:[0,1]
	s_nop 0
	v_pk_fma_f32 v[98:99], v[112:113], v[24:25], v[110:111] op_sel_hi:[1,0,1]
	v_sqrt_f32_e32 v110, s6
	s_nop 0
	v_max_f32_e32 v110, 0x2b8cbccc, v110
	v_rcp_f32_e32 v110, v110
	s_nop 0
	v_mul_f32_e32 v97, v97, v110
	v_mul_f32_e32 v110, 0x3fb8aa3b, v18
	v_exp_f32_e32 v111, v110
	v_mul_f32_e32 v110, 0x3fb8aa3b, v109
	v_exp_f32_e32 v112, v110
	v_mul_f32_e32 v109, 0xbfb8aa3b, v109
	v_exp_f32_e32 v110, v109
	v_mul_f32_e32 v10, v97, v10
	v_mul_f32_e64 v97, v111, -v97
	v_mul_f32_e32 v96, v96, v112
	v_cvt_pk_bf16_f32 v109, v97, s0
	v_cvt_pk_bf16_f32 v96, v96, s0
	v_mul_f32_e32 v97, v10, v110
	v_mul_f32_e32 v111, v0, v110
	v_cvt_pk_bf16_f32 v113, v30, v31
	v_add_f32_e32 v31, v108, v18
	v_cvt_pk_bf16_f32 v97, v97, s0
	v_cvt_pk_bf16_f32 v111, v111, s0
	ds_write_b16 v204, v109
	ds_write_b16 v204, v96 offset:9216
	ds_write_b16 v204, v97 offset:18432
	ds_write_b16 v204, v111 offset:27648
	v_mul_f32_e32 v96, 0x3fb8aa3b, v31
	v_mul_f32_e32 v31, 0xbfb8aa3b, v31
	v_exp_f32_e32 v97, v96
	v_exp_f32_e32 v96, v31
	v_mul_f32_e64 v31, v112, -v116
	v_cvt_pk_bf16_f32 v112, v34, v35
	v_add_f32_e32 v34, v107, v18
	v_mul_f32_e32 v111, v4, v96
	v_mul_f32_e32 v35, 0x3fb8aa3b, v34
	v_cvt_pk_bf16_f32 v31, v31, s0
	v_mul_f32_e32 v94, v94, v97
	v_mul_f32_e32 v108, v12, v96
	v_cvt_pk_bf16_f32 v111, v111, s0
	v_exp_f32_e32 v35, v35
	v_mul_f32_e32 v34, 0xbfb8aa3b, v34
	v_cvt_pk_bf16_f32 v94, v94, s0
	v_cvt_pk_bf16_f32 v108, v108, s0
	ds_write_b16 v204, v31 offset:144
	ds_write_b16 v204, v94 offset:9360
	ds_write_b16 v204, v108 offset:18576
	ds_write_b16 v204, v111 offset:27792
	v_exp_f32_e32 v111, v34
	v_mul_f32_e64 v34, v97, -v115
	v_cvt_pk_bf16_f32 v94, v34, s0
	v_mul_f32_e32 v34, v92, v35
	v_cvt_pk_bf16_f32 v34, v34, s0
	v_mul_f32_e32 v92, v11, v111
	v_mul_f32_e32 v97, v1, v111
	v_cvt_pk_bf16_f32 v92, v92, s0
	v_cvt_pk_bf16_f32 v97, v97, s0
	ds_write_b16 v204, v94 offset:288
	ds_write_b16 v204, v34 offset:9504
	ds_write_b16 v204, v92 offset:18720
	ds_write_b16 v204, v97 offset:27936
	v_add_f32_e32 v34, v106, v18
	v_mul_f32_e32 v92, 0x3fb8aa3b, v34
	v_exp_f32_e32 v92, v92
	v_mul_f32_e32 v34, 0xbfb8aa3b, v34
	v_exp_f32_e32 v97, v34
	v_mul_f32_e64 v34, v35, -v100
	v_cvt_pk_bf16_f32 v100, v34, s0
	v_mul_f32_e32 v34, v90, v92
	v_cvt_pk_bf16_f32 v34, v34, s0
	v_mul_f32_e32 v35, v13, v97
	v_mul_f32_e32 v90, v5, v97
	v_cvt_pk_bf16_f32 v35, v35, s0
	v_cvt_pk_bf16_f32 v90, v90, s0
	ds_write_b16 v204, v100 offset:432
	ds_write_b16 v204, v34 offset:9648
	ds_write_b16 v204, v35 offset:18864
	ds_write_b16 v204, v90 offset:28080
	v_add_f32_e32 v34, v105, v18
	v_mul_f32_e32 v35, 0x3fb8aa3b, v34
	v_exp_f32_e32 v35, v35
	v_mul_f32_e32 v34, 0xbfb8aa3b, v34
	v_exp_f32_e32 v34, v34
	v_mul_f32_e64 v90, v92, -v104
	v_cvt_pk_bf16_f32 v105, v32, v33
	v_add_f32_e32 v32, v103, v18
	v_cvt_pk_bf16_f32 v92, v90, s0
	v_mul_f32_e32 v90, v95, v35
	v_mul_f32_e32 v33, 0x3fb8aa3b, v32
	v_cvt_pk_bf16_f32 v90, v90, s0
	v_mul_f32_e32 v95, v14, v34
	v_mul_f32_e32 v104, v6, v34
	v_exp_f32_e32 v33, v33
	v_mul_f32_e32 v32, 0xbfb8aa3b, v32
	v_cvt_pk_bf16_f32 v95, v95, s0
	v_cvt_pk_bf16_f32 v104, v104, s0
	ds_write_b16 v204, v92 offset:576
	ds_write_b16 v204, v90 offset:9792
	ds_write_b16 v204, v95 offset:19008
	ds_write_b16 v204, v104 offset:28224
	v_exp_f32_e32 v90, v32
	v_mul_f32_e64 v32, v35, -v114
	v_mul_f32_e32 v35, v93, v33
	v_cvt_pk_bf16_f32 v32, v32, s0
	v_cvt_pk_bf16_f32 v35, v35, s0
	v_mul_f32_e32 v93, v16, v90
	v_mul_f32_e32 v95, v8, v90
	v_cvt_pk_bf16_f32 v93, v93, s0
	v_cvt_pk_bf16_f32 v95, v95, s0
	ds_write_b16 v204, v32 offset:720
	ds_write_b16 v204, v35 offset:9936
	ds_write_b16 v204, v93 offset:19152
	ds_write_b16 v204, v95 offset:28368
	v_add_f32_e32 v35, v102, v18
	v_mul_f32_e32 v93, 0x3fb8aa3b, v35
	v_exp_f32_e32 v93, v93
	v_mul_f32_e32 v35, 0xbfb8aa3b, v35
	v_exp_f32_e32 v35, v35
	v_mul_f32_e64 v29, v33, -v29
	v_mul_f32_e32 v33, v91, v93
	v_cvt_pk_bf16_f32 v29, v29, s0
	v_cvt_pk_bf16_f32 v33, v33, s0
	v_mul_f32_e32 v91, v15, v35
	v_mul_f32_e32 v95, v7, v35
	v_add_f32_e32 v18, v101, v18
	v_cvt_pk_bf16_f32 v91, v91, s0
	v_cvt_pk_bf16_f32 v95, v95, s0
	ds_write_b16 v204, v29 offset:864
	ds_write_b16 v204, v33 offset:10080
	ds_write_b16 v204, v91 offset:19296
	ds_write_b16 v204, v95 offset:28512
	v_mul_f32_e32 v33, 0x3fb8aa3b, v18
	v_exp_f32_e32 v33, v33
	v_mul_f32_e32 v18, 0xbfb8aa3b, v18
	v_exp_f32_e32 v91, v18
	v_mul_f32_e64 v18, v93, -v19
	v_mul_f32_e32 v19, v89, v33
	v_cvt_pk_bf16_f32 v18, v18, s0
	v_cvt_pk_bf16_f32 v19, v19, s0
	v_mul_f32_e32 v33, v17, v91
	v_mul_f32_e32 v89, v9, v91
	v_cvt_pk_bf16_f32 v33, v33, s0
	v_cvt_pk_bf16_f32 v89, v89, s0
	ds_write_b16 v204, v18 offset:1008
	ds_write_b16 v204, v19 offset:10224
	ds_write_b16 v204, v33 offset:19440
	ds_write_b16 v204, v89 offset:28656
	v_perm_b32 v30, v31, v109, s96
	v_perm_b32 v31, v100, v94, s96
	v_perm_b32 v33, v18, v29, s96
	v_perm_b32 v32, v32, v92, s96
	v_pk_mul_f32 v[18:19], v[2:3], v[110:111] op_sel_hi:[0,1]
	ds_write_b128 v159, v[30:33] offset:36864
	v_pk_mul_f32 v[30:31], v[2:3], v[96:97] op_sel_hi:[0,1]
	v_pk_mul_f32 v[10:11], v[10:11], v[18:19]
	v_pk_mul_f32 v[0:1], v[0:1], v[18:19]
	v_cvt_pk_bf16_f32 v32, v10, v11
	v_pk_mul_f32 v[10:11], v[12:13], v[30:31]
	v_cvt_pk_bf16_f32 v98, v98, v99
	v_cvt_pk_bf16_f32 v10, v10, v11
	v_perm_b32 v11, v10, v32, s97
	v_perm_b32 v10, v10, v32, s96
	v_pk_mul_f32 v[32:33], v[2:3], v[34:35] op_sel_hi:[0,1]
	v_pk_mul_f32 v[34:35], v[2:3], v[90:91] op_sel_hi:[0,1]
	v_pk_mul_f32 v[12:13], v[14:15], v[32:33]
	s_mov_b64 s[0:1], -1
	v_cvt_pk_bf16_f32 v2, v12, v13
	v_pk_mul_f32 v[12:13], v[16:17], v[34:35]
	s_and_b64 vcc, exec, s[80:81]
	v_cvt_pk_bf16_f32 v12, v12, v13
	v_perm_b32 v13, v12, v2, s97
	v_perm_b32 v12, v12, v2, s96
	v_cvt_pk_bf16_f32 v2, v0, v1
	v_pk_mul_f32 v[0:1], v[4:5], v[30:31]
	ds_write_b128 v159, v[10:13] offset:46080
	v_cvt_pk_bf16_f32 v0, v0, v1
	v_perm_b32 v5, v0, v2, s97
	v_perm_b32 v4, v0, v2, s96
	v_pk_mul_f32 v[0:1], v[6:7], v[32:33]
	v_mov_b32_e32 v12, s55
	v_cvt_pk_bf16_f32 v2, v0, v1
	v_pk_mul_f32 v[0:1], v[8:9], v[34:35]
	s_nop 0
	v_cvt_pk_bf16_f32 v0, v0, v1
	v_perm_b32 v7, v0, v2, s97
	v_perm_b32 v6, v0, v2, s96
	ds_write_b128 v159, v[4:7] offset:55296
	v_perm_b32 v5, v112, v113, s97
	v_perm_b32 v4, v112, v113, s96
	v_perm_b32 v7, v98, v105, s97
	v_perm_b32 v6, v98, v105, s96
	ds_write_b128 v159, v[4:7] offset:64512
	s_waitcnt lgkmcnt(0)
	s_barrier
	s_nop 0
	v_and_b32_e32 v0, 15, v28
	v_and_b32_e32 v1, -16, v28
	v_mad_u32_u24 v12, v0, s76, v12
	v_add_u32_e32 v30, v12, v1
	ds_read_b128 v[8:11], v140
	ds_read_b128 v[4:7], v140 offset:64
	ds_read_b128 v[16:19], v156
	ds_read_b128 v[12:15], v156 offset:64
	v_ashrrev_i32_e32 v2, 4, v28
	v_lshlrev_b32_e32 v29, 2, v2
	v_lshlrev_b32_e32 v2, 3, v2
	v_or_b32_e32 v89, v29, v69
	s_cbranch_vccz .LBB0_700
	s_waitcnt lgkmcnt(1)
	v_mfma_f32_16x16x32_bf16 v[94:97], v[16:19], v[8:11], 0
	s_mov_b64 s[0:1], 0
	s_waitcnt lgkmcnt(0)
	v_mfma_f32_16x16x32_bf16 v[94:97], v[12:15], v[4:7], v[94:97]
	s_nop 7
	v_bfi_b32 v35, v196, v94, v206
	v_and_b32_e32 v90, v166, v95
	v_cvt_pk_bf16_f32 v90, v35, v90
	v_and_b32_e32 v91, v199, v96
	v_and_b32_e32 v93, v202, v97
	v_cvt_pk_bf16_f32 v91, v91, v93
	ds_write_b64 v151, v[90:91]

.LBB0_724:
	v_or_b32_e32 v34, s60, v0
	ds_read_b128 v[8:11], v141
	ds_read_b128 v[4:7], v141 offset:64
	ds_read_b128 v[16:19], v156
	ds_read_b128 v[12:15], v156 offset:64
	s_mov_b64 s[6:7], -1
	s_and_b64 vcc, exec, s[4:5]
	s_cbranch_vccnz .LBB0_728
	s_waitcnt lgkmcnt(1)
	v_mfma_f32_16x16x32_bf16 v[92:95], v[16:19], v[8:11], 0
	s_waitcnt lgkmcnt(0)
	v_mfma_f32_16x16x32_bf16 v[92:95], v[12:15], v[4:7], v[92:95]
	s_nop 7
	v_bfi_b32 v91, v197, v92, v206
	v_and_b32_e32 v89, v167, v93
	v_and_b32_e32 v32, v200, v94
	v_cvt_pk_bf16_f32 v92, v91, v89
	v_and_b32_e32 v31, v203, v95
	v_cvt_pk_bf16_f32 v93, v32, v31
	ds_write_b64 v152, v[92:93]
	v_add_u32_e32 v32, s60, v29
	v_add_u32_e32 v31, s61, v90
	s_cbranch_execz .LBB0_729

.LBB0_727:
	s_waitcnt lgkmcnt(0)
	ds_read_b128 v[12:15], v156 offset:2304
	ds_read_b128 v[16:19], v156 offset:2368
	v_add_u32_e32 v35, 16, v29
	v_cmp_lt_i32_e32 vcc, v35, v34
	s_waitcnt lgkmcnt(1)
	v_mfma_f32_16x16x32_bf16 v[12:15], v[12:15], v[8:11], 0
	v_cndmask_b32_e64 v89, 0, 1, vcc
	v_cmp_le_i32_e32 vcc, v35, v34
	s_waitcnt lgkmcnt(0)
	v_mfma_f32_16x16x32_bf16 v[12:15], v[16:19], v[4:7], v[12:15]
	v_cndmask_b32_e64 v35, 0, 1, vcc
	v_cndmask_b32_e64 v35, v35, v89, s[20:21]
	v_add_u32_e32 v89, 17, v29
	v_and_b32_e32 v35, 1, v35
	s_nop 1
	s_nop 1
	v_bfi_b32 v12, v163, v12, v206
	s_nop 1
	v_and_b32_e32 v13, v164, v13
	v_cvt_pk_bf16_f32 v12, v12, v13
	v_and_b32_e32 v14, v176, v14
	v_and_b32_e32 v15, v178, v15
	v_cvt_pk_bf16_f32 v13, v14, v15
	ds_write_b64 v152, v[12:13] offset:32
	s_cbranch_execnz .LBB0_733
	s_branch .LBB0_731

.LBB0_736:
	s_nop 7
	v_and_b32_e32 v12, v182, v12
	v_and_b32_e32 v13, v184, v13
	v_cvt_pk_bf16_f32 v12, v12, v13
	v_and_b32_e32 v14, v186, v14
	v_and_b32_e32 v15, v188, v15
	v_cvt_pk_bf16_f32 v13, v14, v15
	ds_write_b64 v152, v[12:13] offset:64

.LBB0_740:
	s_nop 7
	v_and_b32_e32 v12, v189, v12
	v_and_b32_e32 v13, v190, v13
	v_cvt_pk_bf16_f32 v12, v12, v13
	v_and_b32_e32 v14, v191, v14
	v_and_b32_e32 v15, v192, v15
	v_cvt_pk_bf16_f32 v13, v14, v15
	ds_write_b64 v152, v[12:13] offset:96
	s_branch .LBB0_750
